# NSA tile loops: next-tile global-load block moved before the per-step LDS wait + barrier (8 sites), on top of bias-read hoist
# speedup vs baseline: 1.0007x; 1.0007x over previous
; #define NSA_GLOAD(R, ti) kv_gload(R, kbase + (size_t)(ti) * 64 * stride, vbase + (size_t)(ti) * 64 * stride, stride)
; template <int MODE> ...
;     ...
;   if (tcur >= 0) kv_lwrite(R0, lds, 0);
;   __syncthreads();
;   NSA_NEXT(t3);
;   if (t3 >= 0) NSA_GLOAD(R0, t3);
.LBB0_357:
	v_readlane_b32 s16, v255, 30
	v_readlane_b32 s17, v255, 31
	s_andn2_b64 vcc, exec, s[16:17]
	s_cbranch_vccnz .Lmy_pb_8
	v_readlane_b32 s16, v255, 33
	v_readlane_b32 s17, v255, 34
	s_waitcnt vmcnt(1)
	v_mov_b32 v50, v179
	s_waitcnt vmcnt(0)
	v_ashrrev_i32_e32 v52, 3, v50
	v_mov_b64_e32 v[48:49], s[16:17]
	v_mad_i64_i32 v[48:49], s[16:17], v52, s61, v[48:49]
	v_readlane_b32 s16, v255, 35
	v_lshlrev_b32_e32 v50, 4, v50
	v_readlane_b32 s17, v255, 36
	v_and_b32_e32 v176, 0x70, v50
	v_lshl_add_u64 v[48:49], v[48:49], 0, v[176:177]
	v_mov_b64_e32 v[50:51], s[16:17]
	v_mad_i64_i32 v[50:51], s[16:17], v52, s61, v[50:51]
	v_lshl_add_u64 v[52:53], v[50:51], 0, v[176:177]
	global_load_dwordx4 v[48:51], v[48:49], off
	s_nop 0
	global_load_dwordx4 v[52:55], v[52:53], off
.Lmy_pb_8:
	s_waitcnt lgkmcnt(0)
	s_barrier

.LBB0_375:
	s_cmp_gt_i32 s75, 3
	s_cselect_b32 s62, s63, -1
	s_cmp_lt_i32 s62, 0
	s_cbranch_scc1 .Lmy_pb_7
	s_mul_i32 s36, s62, 0x50000
	s_mul_hi_u32 s17, s62, 0x50000
	s_add_u32 s30, s67, s36
	s_addc_u32 s31, s68, s17
	s_add_u32 s36, s69, s36
	s_waitcnt vmcnt(1)
	v_mov_b32 v58, v179
	s_addc_u32 s37, s70, s17
	s_waitcnt vmcnt(0)
	v_ashrrev_i32_e32 v60, 3, v58
	v_lshlrev_b32_e32 v58, 4, v58
	v_mov_b64_e32 v[56:57], s[30:31]
	v_and_b32_e32 v176, 0x70, v58
	v_mov_b64_e32 v[58:59], s[36:37]
	v_mad_i64_i32 v[56:57], s[30:31], v60, s61, v[56:57]
	v_mad_i64_i32 v[58:59], s[30:31], v60, s61, v[58:59]
	v_lshl_add_u64 v[56:57], v[56:57], 0, v[176:177]
	v_lshl_add_u64 v[60:61], v[58:59], 0, v[176:177]
	global_load_dwordx4 v[56:59], v[56:57], off
	s_nop 0
	global_load_dwordx4 v[60:63], v[60:61], off

.LBB0_393:
	s_add_i32 s17, s63, 1
	s_cmp_gt_i32 s75, 4
	s_cselect_b32 s16, s17, -1
	s_cmp_lt_i32 s16, 0
	s_cbranch_scc1 .Lmy_pb_6
	s_mul_i32 s36, s16, 0x50000
	s_mul_hi_u32 s37, s16, 0x50000
	s_add_u32 s30, s67, s36
	s_addc_u32 s31, s68, s37
	s_add_u32 s36, s69, s36
	s_waitcnt vmcnt(1)
	v_mov_b32 v66, v179
	s_addc_u32 s37, s70, s37
	s_waitcnt vmcnt(0)
	v_ashrrev_i32_e32 v68, 3, v66
	v_lshlrev_b32_e32 v66, 4, v66
	v_mov_b64_e32 v[64:65], s[30:31]
	v_and_b32_e32 v176, 0x70, v66
	v_mov_b64_e32 v[66:67], s[36:37]
	v_mad_i64_i32 v[64:65], s[30:31], v68, s61, v[64:65]
	v_mad_i64_i32 v[66:67], s[30:31], v68, s61, v[66:67]
	v_lshl_add_u64 v[64:65], v[64:65], 0, v[176:177]
	v_lshl_add_u64 v[68:69], v[66:67], 0, v[176:177]
	global_load_dwordx4 v[64:67], v[64:65], off
	s_nop 0
	global_load_dwordx4 v[68:71], v[68:69], off

.LBB0_410:
	s_add_i32 s17, s17, 1
	s_cmp_gt_i32 s75, 5
	s_cselect_b32 s73, s17, -1
	s_cmp_lt_i32 s73, 0
	s_cbranch_scc1 .Lmy_pb_5
	s_mul_i32 s36, s73, 0x50000
	s_mul_hi_u32 s37, s73, 0x50000
	s_add_u32 s30, s67, s36
	s_addc_u32 s31, s68, s37
	s_add_u32 s36, s69, s36
	s_waitcnt vmcnt(1)
	v_mov_b32 v50, v179
	s_addc_u32 s37, s70, s37
	s_waitcnt vmcnt(0)
	v_ashrrev_i32_e32 v52, 3, v50
	v_lshlrev_b32_e32 v50, 4, v50
	v_mov_b64_e32 v[48:49], s[30:31]
	v_and_b32_e32 v176, 0x70, v50
	v_mov_b64_e32 v[50:51], s[36:37]
	v_mad_i64_i32 v[48:49], s[30:31], v52, s61, v[48:49]
	v_mad_i64_i32 v[50:51], s[30:31], v52, s61, v[50:51]
	v_lshl_add_u64 v[48:49], v[48:49], 0, v[176:177]
	v_lshl_add_u64 v[52:53], v[50:51], 0, v[176:177]
	global_load_dwordx4 v[48:51], v[48:49], off
	s_nop 0
	global_load_dwordx4 v[52:55], v[52:53], off

; #define NSA_GLOAD(R, ti) kv_gload(R, kbase + (size_t)(ti) * 64 * stride, vbase + (size_t)(ti) * 64 * stride, stride)
; template <int MODE> ...
;     ...
;   if (tcur >= 0) kv_lwrite(R0, lds, 0);
;   __syncthreads();
;   NSA_NEXT(t3);
;   if (t3 >= 0) NSA_GLOAD(R0, t3);
.LBB0_431:
	s_andn2_b64 vcc, exec, s[86:87]
	s_cbranch_vccnz .Lmy_pb_4
	v_readlane_b32 s16, v255, 48
	s_waitcnt vmcnt(1)
	v_mov_b32 v50, v179
	v_readlane_b32 s17, v255, 49
	v_ashrrev_i32_e32 v51, 3, v50
	v_lshlrev_b32_e32 v50, 4, v50
	v_mov_b64_e32 v[48:49], s[16:17]
	v_mad_i64_i32 v[48:49], s[16:17], v51, s61, v[48:49]
	v_and_b32_e32 v176, 0x70, v50
	s_waitcnt vmcnt(0)
	v_lshl_add_u64 v[52:53], v[48:49], 0, v[176:177]
	global_load_dwordx4 v[48:51], v[52:53], off offset:3584
	s_nop 0
	global_load_dwordx4 v[52:55], v[52:53], off offset:3840

.LBB0_450:
	s_cmp_eq_u64 s[42:43], 0
	s_cselect_b64 s[94:95], -1, 0
	s_ff1_i32_b64 s64, s[42:43]
	s_and_b64 vcc, exec, s[94:95]
	s_cbranch_vccnz .Lmy_pb_3
	s_mul_i32 s46, s64, 0x28000
	s_lshl_b64 s[30:31], s[46:47], 1
	s_add_u32 s30, s65, s30
	s_addc_u32 s31, s66, s31
	v_mov_b32 v18, v179
	v_mov_b64_e32 v[16:17], s[30:31]
	v_ashrrev_i32_e32 v19, 3, v18
	v_lshlrev_b32_e32 v18, 4, v18
	v_mad_i64_i32 v[16:17], s[30:31], v19, s61, v[16:17]
	v_and_b32_e32 v176, 0x70, v18
	v_lshl_add_u64 v[16:17], v[16:17], 0, v[176:177]
	global_load_dwordx4 v[56:59], v[16:17], off offset:3584
	global_load_dwordx4 v[60:63], v[16:17], off offset:3840

.LBB0_467:
	s_add_u32 s16, s42, -1
	s_addc_u32 s17, s43, -1
	s_and_b64 s[96:97], s[16:17], s[42:43]
	s_cmp_eq_u64 s[96:97], 0
	s_cselect_b64 s[30:31], -1, 0
	s_ff1_i32_b64 s17, s[96:97]
	s_and_b64 vcc, exec, s[30:31]
	s_cbranch_vccnz .Lmy_pb_2
	s_mul_i32 s46, s17, 0x28000
	s_lshl_b64 s[36:37], s[46:47], 1
	s_add_u32 s36, s65, s36
	s_addc_u32 s37, s66, s37
	v_mov_b32 v18, v179
	v_mov_b64_e32 v[16:17], s[36:37]
	v_ashrrev_i32_e32 v19, 3, v18
	v_lshlrev_b32_e32 v18, 4, v18
	v_mad_i64_i32 v[16:17], s[36:37], v19, s61, v[16:17]
	v_and_b32_e32 v176, 0x70, v18
	v_lshl_add_u64 v[16:17], v[16:17], 0, v[176:177]
	global_load_dwordx4 v[64:67], v[16:17], off offset:3584
	global_load_dwordx4 v[68:71], v[16:17], off offset:3840

.LBB0_484:
	s_add_u32 s36, s96, -1
	s_addc_u32 s37, s97, -1
	s_and_b64 s[36:37], s[36:37], s[96:97]
	s_cmp_eq_u64 s[36:37], 0
	s_cselect_b64 s[42:43], -1, 0
	s_ff1_i32_b64 s16, s[36:37]
	s_and_b64 vcc, exec, s[42:43]
	s_cbranch_vccnz .Lmy_pb_1
	s_mul_i32 s46, s16, 0x28000
	s_lshl_b64 s[62:63], s[46:47], 1
	s_add_u32 s62, s65, s62
	s_addc_u32 s63, s66, s63
	s_waitcnt vmcnt(1)
	v_mov_b32 v50, v179
	v_mov_b64_e32 v[48:49], s[62:63]
	v_ashrrev_i32_e32 v51, 3, v50
	v_lshlrev_b32_e32 v50, 4, v50
	v_mad_i64_i32 v[48:49], s[62:63], v51, s61, v[48:49]
	v_and_b32_e32 v176, 0x70, v50
	s_waitcnt vmcnt(0)
	v_lshl_add_u64 v[52:53], v[48:49], 0, v[176:177]
	global_load_dwordx4 v[48:51], v[52:53], off offset:3584
	s_nop 0
	global_load_dwordx4 v[52:55], v[52:53], off offset:3840
